# selected-branch per-query loop rewritten slot-wise with double-buffered K fragments (prefetch one slot ahead)
# speedup vs baseline: 1.0927x; 1.0078x over previous
; __device__ __forceinline__ void nsa_wave(CArgs* Ap, int l, int b, int g, int tq0, const LAS float* lut, LAS float* imp, int lane) {
;     ...
;         const int nh = 2 * nvalid, h0 = 2 * ns;
;         long kq[4][2][2], vq[4][4];
;         if (h0 < nh) {
; #pragma unroll
;             for (int q2 = 0; q2 < 4; ++q2) { int j = __builtin_amdgcn_readlane(selreg, 16 * q2 + ns); j = j < 0 ? 0 : j; load_kh8(kq[q2], Ks8 + (size_t)j * 4096, 0, lane); load_vh8(vq[q2], Vs8 + (size_t)j * 4096, 0, lane); } }
;         for (int hs = h0; hs < nh; ++hs) {
;             const int s = hs >> 1, hh = hs & 1;
;             const int jm = __shfl(selreg, 16 * qi + s);
;             f32x4 acc[2];
;             acc[0] = (f32x4){0.f, 0.f, 0.f, 0.f}; acc[1] = (f32x4){0.f, 0.f, 0.f, 0.f};
; #pragma unroll
;             for (int q2 = 0; q2 < 4; ++q2) { long qm[2]; qm[0] = (qi == q2) ? q8[0] : 0l; qm[1] = (qi == q2) ? q8[1] : 0l; qk_acch8(acc, kq[q2], qm); }
;             const bool more = hs + 1 < nh; const int s1 = (hs + 1) >> 1, h1 = (hs + 1) & 1;
;             int jn[4];
; #pragma unroll
;             for (int q2 = 0; q2 < 4; ++q2) { int j = more ? __builtin_amdgcn_readlane(selreg, 16 * q2 + s1) : 0; jn[q2] = j < 0 ? 0 : j; }
;             if (more) {
; #pragma unroll
;                 for (int q2 = 0; q2 < 4; ++q2) load_kh8(kq[q2], Ks8 + (size_t)jn[q2] * 4096, h1, lane); }
.LBB0_1259:
	s_lshl_b32 s22, s22, 1
	s_cmp_gt_i32 s23, s22
	s_cbranch_scc1 .LBB0_1279
	s_mov_b32 s32, s24
	s_lshr_b32 s42, s22, 1
	s_add_i32 s42, s42, 1
	v_or_b32_e32 v229, 0x800, v84
	v_readlane_b32 s25, v210, s32
	s_max_i32 s72, s25, 0
	s_lshl_b64 s[36:37], s[72:73], 12
	s_add_i32 s25, s32, 16
	v_readlane_b32 s25, v210, s25
	s_max_i32 s72, s25, 0
	s_lshl_b64 s[38:39], s[72:73], 12
	s_xor_b32 s25, s32, 32
	v_readlane_b32 s25, v210, s25
	s_max_i32 s72, s25, 0
	s_lshl_b64 s[40:41], s[72:73], 12
	s_add_i32 s25, s32, 48
	v_readlane_b32 s25, v210, s25
	s_max_i32 s72, s25, 0
	s_lshl_b64 s[84:85], s[72:73], 12
	s_add_u32 s48, s96, s36
	s_addc_u32 s49, s97, s37
	global_load_dwordx4 v[32:35], v84, s[48:49]
	global_load_dwordx4 v[36:39], v84, s[48:49] offset:1024
	s_add_u32 s48, s96, s38
	s_addc_u32 s49, s97, s39
	global_load_dwordx4 v[48:51], v84, s[48:49]
	global_load_dwordx4 v[52:55], v84, s[48:49] offset:1024
	s_add_u32 s48, s96, s40
	s_addc_u32 s49, s97, s41
	global_load_dwordx4 v[64:67], v84, s[48:49]
	global_load_dwordx4 v[68:71], v84, s[48:49] offset:1024
	s_add_u32 s48, s96, s84
	s_addc_u32 s49, s97, s85
	global_load_dwordx4 v[112:115], v84, s[48:49]
	global_load_dwordx4 v[116:119], v84, s[48:49] offset:1024
	s_add_u32 s48, s96, s36
	s_addc_u32 s49, s97, s37
	global_load_dwordx4 v[184:187], v229, s[48:49]
	global_load_dwordx4 v[188:191], v229, s[48:49] offset:1024
	s_add_u32 s48, s96, s38
	s_addc_u32 s49, s97, s39
	global_load_dwordx4 v[192:195], v229, s[48:49]
	global_load_dwordx4 v[196:199], v229, s[48:49] offset:1024
	s_add_u32 s48, s96, s40
	s_addc_u32 s49, s97, s41
	global_load_dwordx4 v[230:233], v229, s[48:49]
	global_load_dwordx4 v[234:237], v229, s[48:49] offset:1024
	s_add_u32 s48, s96, s84
	s_addc_u32 s49, s97, s85
	global_load_dwordx4 v[238:241], v229, s[48:49]
	global_load_dwordx4 v[242:245], v229, s[48:49] offset:1024
	s_add_u32 s48, s0, s36
	s_addc_u32 s49, s1, s37
	global_load_dwordx4 v[40:43], v84, s[48:49]
	global_load_dwordx4 v[44:47], v84, s[48:49] offset:1024
	s_add_u32 s48, s0, s38
	s_addc_u32 s49, s1, s39
	global_load_dwordx4 v[56:59], v84, s[48:49]
	global_load_dwordx4 v[60:63], v84, s[48:49] offset:1024
	s_add_u32 s48, s0, s40
	s_addc_u32 s49, s1, s41
	global_load_dwordx4 v[74:77], v84, s[48:49]
	global_load_dwordx4 v[78:81], v84, s[48:49] offset:1024
	s_add_u32 s48, s0, s84
	s_addc_u32 s49, s1, s85
	global_load_dwordx4 v[106:109], v84, s[48:49]
	global_load_dwordx4 v[122:125], v84, s[48:49] offset:1024
	v_cndmask_b32_e64 v83, 0, v103, s[6:7]
	v_cndmask_b32_e64 v82, 0, v102, s[6:7]
	v_cndmask_b32_e64 v99, 0, v103, s[8:9]
	v_cndmask_b32_e64 v98, 0, v102, s[8:9]
	v_cndmask_b32_e64 v101, 0, v103, s[10:11]
	v_cndmask_b32_e64 v100, 0, v102, s[10:11]
	v_cndmask_b32_e64 v103, 0, v103, s[12:13]
	v_cndmask_b32_e64 v102, 0, v102, s[12:13]
	v_cndmask_b32_e64 v105, 0, v127, s[6:7]
	v_cndmask_b32_e64 v104, 0, v126, s[6:7]
	v_cndmask_b32_e64 v111, 0, v127, s[8:9]
	v_cndmask_b32_e64 v110, 0, v126, s[8:9]
	v_cndmask_b32_e64 v121, 0, v127, s[10:11]
	v_cndmask_b32_e64 v120, 0, v126, s[10:11]
	v_cndmask_b32_e64 v127, 0, v127, s[12:13]
	v_cndmask_b32_e64 v126, 0, v126, s[12:13]
	s_lshl_b32 s24, s24, 6
	s_add_i32 s25, s32, 1
	s_cmp_lt_i32 s25, s42
	s_cbranch_scc0 .Lsl_last
.Lsl_steady:
	s_add_i32 s23, s32, 1
	v_readlane_b32 s25, v210, s23
	s_max_i32 s72, s25, 0
	s_lshl_b64 s[26:27], s[72:73], 12
	s_add_i32 s25, s23, 16
	v_readlane_b32 s25, v210, s25
	s_max_i32 s72, s25, 0
	s_lshl_b64 s[28:29], s[72:73], 12
	s_xor_b32 s25, s23, 32
	v_readlane_b32 s25, v210, s25
	s_max_i32 s72, s25, 0
	s_lshl_b64 s[30:31], s[72:73], 12
	s_add_i32 s25, s23, 48
	v_readlane_b32 s25, v210, s25
	s_max_i32 s72, s25, 0
	s_lshl_b64 s[34:35], s[72:73], 12
	s_waitcnt vmcnt(23)
	v_mfma_f32_16x16x32_fp8_fp8 v[24:27], v[32:33], v[82:83], 0
	v_add_u32_e32 v150, s32, v201
	v_and_or_b32 v150, v150, 63, v73
	s_waitcnt vmcnt(22)
	v_mfma_f32_16x16x32_fp8_fp8 v[28:31], v[36:37], v[82:83], 0
	v_lshlrev_b32_e32 v150, 2, v150
	ds_bpermute_b32 v214, v150, v210
	v_mfma_f32_16x16x32_fp8_fp8 v[24:27], v[34:35], v[104:105], v[24:27]
	v_mfma_f32_16x16x32_fp8_fp8 v[28:31], v[38:39], v[104:105], v[28:31]
	s_waitcnt vmcnt(21)
	v_mfma_f32_16x16x32_fp8_fp8 v[24:27], v[48:49], v[98:99], v[24:27]
	s_waitcnt vmcnt(20)
	v_mfma_f32_16x16x32_fp8_fp8 v[28:31], v[52:53], v[98:99], v[28:31]
	v_mfma_f32_16x16x32_fp8_fp8 v[24:27], v[50:51], v[110:111], v[24:27]
	v_mfma_f32_16x16x32_fp8_fp8 v[28:31], v[54:55], v[110:111], v[28:31]
	s_waitcnt vmcnt(19)
	v_mfma_f32_16x16x32_fp8_fp8 v[24:27], v[64:65], v[100:101], v[24:27]
	s_waitcnt vmcnt(18)
	v_mfma_f32_16x16x32_fp8_fp8 v[28:31], v[68:69], v[100:101], v[28:31]
	v_mfma_f32_16x16x32_fp8_fp8 v[24:27], v[66:67], v[120:121], v[24:27]
	v_mfma_f32_16x16x32_fp8_fp8 v[28:31], v[70:71], v[120:121], v[28:31]
	s_waitcnt vmcnt(17)
	v_mfma_f32_16x16x32_fp8_fp8 v[24:27], v[112:113], v[102:103], v[24:27]
	s_waitcnt vmcnt(16)
	v_mfma_f32_16x16x32_fp8_fp8 v[28:31], v[116:117], v[102:103], v[28:31]
	v_mfma_f32_16x16x32_fp8_fp8 v[24:27], v[114:115], v[126:127], v[24:27]
	v_mfma_f32_16x16x32_fp8_fp8 v[28:31], v[118:119], v[126:127], v[28:31]
	s_add_u32 s48, s96, s26
	s_addc_u32 s49, s97, s27
	global_load_dwordx4 v[32:35], v84, s[48:49]
	global_load_dwordx4 v[36:39], v84, s[48:49] offset:1024
	s_add_u32 s48, s96, s28
	s_addc_u32 s49, s97, s29
	global_load_dwordx4 v[48:51], v84, s[48:49]
	global_load_dwordx4 v[52:55], v84, s[48:49] offset:1024
	s_add_u32 s48, s96, s30
	s_addc_u32 s49, s97, s31
	global_load_dwordx4 v[64:67], v84, s[48:49]
	global_load_dwordx4 v[68:71], v84, s[48:49] offset:1024
	s_add_u32 s48, s96, s34
	s_addc_u32 s49, s97, s35
	global_load_dwordx4 v[112:115], v84, s[48:49]
	global_load_dwordx4 v[116:119], v84, s[48:49] offset:1024

; __device__ __forceinline__ void nsa_wave(CArgs* Ap, int l, int b, int g, int tq0, const LAS float* lut, LAS float* imp, int lane) {
;     ...
;         for (int hs = h0; hs < nh; ++hs) {
;             const int s = hs >> 1, hh = hs & 1;
;             const int jm = __shfl(selreg, 16 * qi + s);
;             f32x4 acc[2];
;             acc[0] = (f32x4){0.f, 0.f, 0.f, 0.f}; acc[1] = (f32x4){0.f, 0.f, 0.f, 0.f};
; #pragma unroll
;             for (int q2 = 0; q2 < 4; ++q2) { long qm[2]; qm[0] = (qi == q2) ? q8[0] : 0l; qm[1] = (qi == q2) ? q8[1] : 0l; qk_acch8(acc, kq[q2], qm); }
;             const bool more = hs + 1 < nh; const int s1 = (hs + 1) >> 1, h1 = (hs + 1) & 1;
;             int jn[4];
; #pragma unroll
;             for (int q2 = 0; q2 < 4; ++q2) { int j = more ? __builtin_amdgcn_readlane(selreg, 16 * q2 + s1) : 0; jn[q2] = j < 0 ? 0 : j; }
;             if (more) {
; #pragma unroll
;                 for (int q2 = 0; q2 < 4; ++q2) load_kh8(kq[q2], Ks8 + (size_t)jn[q2] * 4096, h1, lane); }
;             if (__all(jm >= 0 && t - (jm * 64 + 32 * hh + 31) >= 1023)) softmax_half_far(acc, lutg, st, Od);
;             else { bf16x8 pB; softmax_half<1>(acc, (jm < 0 ? 0 : jm) * 64 + 32 * hh, jm >= 0, t, g4, lutg, st, Od, pB); }
;             const long p8 = p_to_fp8(acc);
; #pragma unroll
;             for (int q2 = 0; q2 < 4; ++q2) { const long pm = (qi == q2) ? p8 : 0l; pv_acch8(Od, vq[q2], pm); }
;             if (more) {
; #pragma unroll
;                 for (int q2 = 0; q2 < 4; ++q2) load_vh8(vq[q2], Vs8 + (size_t)jn[q2] * 4096, h1, lane); }
.Lsla_1275:
	v_sub_f32_e32 v24, v144, v213
	v_mul_f32_e32 v25, 0x43800000, v216
	v_mul_f32_e32 v26, 0x43800000, v217
	v_mul_f32_e32 v29, 0x43800000, v220
	v_mul_f32_e32 v30, 0x43800000, v221
	v_mov_b32_e32 v31, 0
	v_mov_b32_e32 v144, 0
	v_cvt_pk_fp8_f32 v144, v29, v30
	v_cvt_pk_fp8_f32 v31, v25, v26
	v_mul_f32_e32 v24, 0x3fb8aa3b, v24
	v_mul_f32_e32 v27, 0x43800000, v218
	v_mul_f32_e32 v28, 0x43800000, v219
	v_mul_f32_e32 v25, 0x43800000, v222
	v_mul_f32_e32 v26, 0x43800000, v223
	v_exp_f32_e32 v24, v24
	v_cvt_pk_fp8_f32 v144, v25, v26 op_sel:[0,0,1]
	v_cvt_pk_fp8_f32 v31, v27, v28 op_sel:[0,0,1]
	s_and_b64 vcc, exec, s[46:47]
	v_pk_mul_f32 v[22:23], v[22:23], v[24:25] op_sel_hi:[1,0]
	v_pk_mul_f32 v[20:21], v[20:21], v[24:25] op_sel_hi:[1,0]
	v_cndmask_b32_e64 v27, 0, v144, s[6:7]
	v_cndmask_b32_e64 v26, 0, v31, s[6:7]
	v_pk_mul_f32 v[18:19], v[18:19], v[24:25] op_sel_hi:[1,0]
	v_pk_mul_f32 v[16:17], v[16:17], v[24:25] op_sel_hi:[1,0]
	v_pk_mul_f32 v[14:15], v[14:15], v[24:25] op_sel_hi:[1,0]
	v_pk_mul_f32 v[12:13], v[12:13], v[24:25] op_sel_hi:[1,0]
	v_pk_mul_f32 v[10:11], v[10:11], v[24:25] op_sel_hi:[1,0]
	v_pk_mul_f32 v[8:9], v[8:9], v[24:25] op_sel_hi:[1,0]
	s_waitcnt vmcnt(15)
	s_nop 0
	v_mfma_f32_16x16x32_fp8_fp8 v[20:23], v[40:41], v[26:27], v[20:23]
	v_mfma_f32_16x16x32_fp8_fp8 v[16:19], v[42:43], v[26:27], v[16:19]
	s_waitcnt vmcnt(14)
	v_mfma_f32_16x16x32_fp8_fp8 v[12:15], v[44:45], v[26:27], v[12:15]
	v_mfma_f32_16x16x32_fp8_fp8 v[8:11], v[46:47], v[26:27], v[8:11]
	v_cndmask_b32_e64 v27, 0, v144, s[8:9]
	v_cndmask_b32_e64 v26, 0, v31, s[8:9]
	s_waitcnt vmcnt(13)
	s_nop 0
	v_mfma_f32_16x16x32_fp8_fp8 v[20:23], v[56:57], v[26:27], v[20:23]
	v_mfma_f32_16x16x32_fp8_fp8 v[16:19], v[58:59], v[26:27], v[16:19]
	s_waitcnt vmcnt(12)
	v_mfma_f32_16x16x32_fp8_fp8 v[12:15], v[60:61], v[26:27], v[12:15]
	v_mfma_f32_16x16x32_fp8_fp8 v[8:11], v[62:63], v[26:27], v[8:11]
	v_cndmask_b32_e64 v27, 0, v144, s[10:11]
	v_cndmask_b32_e64 v26, 0, v31, s[10:11]
	s_waitcnt vmcnt(11)
	s_nop 0
	v_mfma_f32_16x16x32_fp8_fp8 v[20:23], v[74:75], v[26:27], v[20:23]
	v_mfma_f32_16x16x32_fp8_fp8 v[16:19], v[76:77], v[26:27], v[16:19]
	s_waitcnt vmcnt(10)
	v_mfma_f32_16x16x32_fp8_fp8 v[12:15], v[78:79], v[26:27], v[12:15]
	v_mfma_f32_16x16x32_fp8_fp8 v[8:11], v[80:81], v[26:27], v[8:11]
	v_cndmask_b32_e64 v27, 0, v144, s[12:13]
	v_cndmask_b32_e64 v26, 0, v31, s[12:13]
	s_waitcnt vmcnt(9)
	s_nop 0
	v_mfma_f32_16x16x32_fp8_fp8 v[20:23], v[106:107], v[26:27], v[20:23]
	v_mfma_f32_16x16x32_fp8_fp8 v[16:19], v[108:109], v[26:27], v[16:19]
	s_waitcnt vmcnt(8)
	v_mfma_f32_16x16x32_fp8_fp8 v[12:15], v[122:123], v[26:27], v[12:15]
	v_mfma_f32_16x16x32_fp8_fp8 v[8:11], v[124:125], v[26:27], v[8:11]
	s_add_u32 s48, s0, s36
	s_addc_u32 s49, s1, s37
	global_load_dwordx4 v[40:43], v229, s[48:49]
	global_load_dwordx4 v[44:47], v229, s[48:49] offset:1024
	s_add_u32 s48, s0, s38
	s_addc_u32 s49, s1, s39
	global_load_dwordx4 v[56:59], v229, s[48:49]
	global_load_dwordx4 v[60:63], v229, s[48:49] offset:1024
	s_add_u32 s48, s0, s40
	s_addc_u32 s49, s1, s41
	global_load_dwordx4 v[74:77], v229, s[48:49]
	global_load_dwordx4 v[78:81], v229, s[48:49] offset:1024
	s_add_u32 s48, s0, s84
	s_addc_u32 s49, s1, s85
	global_load_dwordx4 v[106:109], v229, s[48:49]
	global_load_dwordx4 v[122:125], v229, s[48:49] offset:1024
	v_fmac_f32_e32 v215, v212, v24
	s_add_i32 s24, s24, 32
	s_nop 0
	v_mov_b32_e32 v212, v215
	v_mov_b32_e32 v144, v213
	s_waitcnt vmcnt(16)
	v_mfma_f32_16x16x32_fp8_fp8 v[24:27], v[184:185], v[82:83], 0
	v_add_u32_e32 v150, s32, v201
	v_and_or_b32 v150, v150, 63, v73
	v_mfma_f32_16x16x32_fp8_fp8 v[28:31], v[188:189], v[82:83], 0
	v_lshlrev_b32_e32 v150, 2, v150
	ds_bpermute_b32 v214, v150, v210
	v_mfma_f32_16x16x32_fp8_fp8 v[24:27], v[186:187], v[104:105], v[24:27]
	v_mfma_f32_16x16x32_fp8_fp8 v[28:31], v[190:191], v[104:105], v[28:31]
	v_mfma_f32_16x16x32_fp8_fp8 v[24:27], v[192:193], v[98:99], v[24:27]
	v_mfma_f32_16x16x32_fp8_fp8 v[28:31], v[196:197], v[98:99], v[28:31]
	v_mfma_f32_16x16x32_fp8_fp8 v[24:27], v[194:195], v[110:111], v[24:27]
	v_mfma_f32_16x16x32_fp8_fp8 v[28:31], v[198:199], v[110:111], v[28:31]
	v_mfma_f32_16x16x32_fp8_fp8 v[24:27], v[230:231], v[100:101], v[24:27]
	v_mfma_f32_16x16x32_fp8_fp8 v[28:31], v[234:235], v[100:101], v[28:31]
	v_mfma_f32_16x16x32_fp8_fp8 v[24:27], v[232:233], v[120:121], v[24:27]
	v_mfma_f32_16x16x32_fp8_fp8 v[28:31], v[236:237], v[120:121], v[28:31]
	v_mfma_f32_16x16x32_fp8_fp8 v[24:27], v[238:239], v[102:103], v[24:27]
	v_mfma_f32_16x16x32_fp8_fp8 v[28:31], v[242:243], v[102:103], v[28:31]
	v_mfma_f32_16x16x32_fp8_fp8 v[24:27], v[240:241], v[126:127], v[24:27]
	v_mfma_f32_16x16x32_fp8_fp8 v[28:31], v[244:245], v[126:127], v[28:31]
	s_add_u32 s48, s96, s26
	s_addc_u32 s49, s97, s27
	global_load_dwordx4 v[184:187], v229, s[48:49]
	global_load_dwordx4 v[188:191], v229, s[48:49] offset:1024
	s_add_u32 s48, s96, s28
	s_addc_u32 s49, s97, s29
	global_load_dwordx4 v[192:195], v229, s[48:49]
	global_load_dwordx4 v[196:199], v229, s[48:49] offset:1024
	s_add_u32 s48, s96, s30
	s_addc_u32 s49, s97, s31
	global_load_dwordx4 v[230:233], v229, s[48:49]
	global_load_dwordx4 v[234:237], v229, s[48:49] offset:1024
	s_add_u32 s48, s96, s34
	s_addc_u32 s49, s97, s35
	global_load_dwordx4 v[238:241], v229, s[48:49]
	global_load_dwordx4 v[242:245], v229, s[48:49] offset:1024

; __device__ __forceinline__ void nsa_wave(CArgs* Ap, int l, int b, int g, int tq0, const LAS float* lut, LAS float* imp, int lane) {
;     ...
;         for (int hs = h0; hs < nh; ++hs) {
;             const int s = hs >> 1, hh = hs & 1;
;             const int jm = __shfl(selreg, 16 * qi + s);
;             f32x4 acc[2];
;             acc[0] = (f32x4){0.f, 0.f, 0.f, 0.f}; acc[1] = (f32x4){0.f, 0.f, 0.f, 0.f};
; #pragma unroll
;             for (int q2 = 0; q2 < 4; ++q2) { long qm[2]; qm[0] = (qi == q2) ? q8[0] : 0l; qm[1] = (qi == q2) ? q8[1] : 0l; qk_acch8(acc, kq[q2], qm); }
;             const bool more = hs + 1 < nh; const int s1 = (hs + 1) >> 1, h1 = (hs + 1) & 1;
;             int jn[4];
; #pragma unroll
;             for (int q2 = 0; q2 < 4; ++q2) { int j = more ? __builtin_amdgcn_readlane(selreg, 16 * q2 + s1) : 0; jn[q2] = j < 0 ? 0 : j; }
;             if (more) {
; #pragma unroll
;                 for (int q2 = 0; q2 < 4; ++q2) load_kh8(kq[q2], Ks8 + (size_t)jn[q2] * 4096, h1, lane); }
;             if (__all(jm >= 0 && t - (jm * 64 + 32 * hh + 31) >= 1023)) softmax_half_far(acc, lutg, st, Od);
;             else { bf16x8 pB; softmax_half<1>(acc, (jm < 0 ? 0 : jm) * 64 + 32 * hh, jm >= 0, t, g4, lutg, st, Od, pB); }
;             const long p8 = p_to_fp8(acc);
; #pragma unroll
;             for (int q2 = 0; q2 < 4; ++q2) { const long pm = (qi == q2) ? p8 : 0l; pv_acch8(Od, vq[q2], pm); }
;             if (more) {
; #pragma unroll
;                 for (int q2 = 0; q2 < 4; ++q2) load_vh8(vq[q2], Vs8 + (size_t)jn[q2] * 4096, h1, lane); }
;         }
.Lslb_1275:
	v_sub_f32_e32 v24, v144, v213
	v_mul_f32_e32 v25, 0x43800000, v216
	v_mul_f32_e32 v26, 0x43800000, v217
	v_mul_f32_e32 v29, 0x43800000, v220
	v_mul_f32_e32 v30, 0x43800000, v221
	v_mov_b32_e32 v31, 0
	v_mov_b32_e32 v144, 0
	v_cvt_pk_fp8_f32 v144, v29, v30
	v_cvt_pk_fp8_f32 v31, v25, v26
	v_mul_f32_e32 v24, 0x3fb8aa3b, v24
	v_mul_f32_e32 v27, 0x43800000, v218
	v_mul_f32_e32 v28, 0x43800000, v219
	v_mul_f32_e32 v25, 0x43800000, v222
	v_mul_f32_e32 v26, 0x43800000, v223
	v_exp_f32_e32 v24, v24
	v_cvt_pk_fp8_f32 v144, v25, v26 op_sel:[0,0,1]
	v_cvt_pk_fp8_f32 v31, v27, v28 op_sel:[0,0,1]
	s_and_b64 vcc, exec, s[46:47]
	v_pk_mul_f32 v[22:23], v[22:23], v[24:25] op_sel_hi:[1,0]
	v_pk_mul_f32 v[20:21], v[20:21], v[24:25] op_sel_hi:[1,0]
	v_cndmask_b32_e64 v27, 0, v144, s[6:7]
	v_cndmask_b32_e64 v26, 0, v31, s[6:7]
	v_pk_mul_f32 v[18:19], v[18:19], v[24:25] op_sel_hi:[1,0]
	v_pk_mul_f32 v[16:17], v[16:17], v[24:25] op_sel_hi:[1,0]
	v_pk_mul_f32 v[14:15], v[14:15], v[24:25] op_sel_hi:[1,0]
	v_pk_mul_f32 v[12:13], v[12:13], v[24:25] op_sel_hi:[1,0]
	v_pk_mul_f32 v[10:11], v[10:11], v[24:25] op_sel_hi:[1,0]
	v_pk_mul_f32 v[8:9], v[8:9], v[24:25] op_sel_hi:[1,0]
	s_waitcnt vmcnt(15)
	s_nop 0
	v_mfma_f32_16x16x32_fp8_fp8 v[20:23], v[40:41], v[26:27], v[20:23]
	v_mfma_f32_16x16x32_fp8_fp8 v[16:19], v[42:43], v[26:27], v[16:19]
	s_waitcnt vmcnt(14)
	v_mfma_f32_16x16x32_fp8_fp8 v[12:15], v[44:45], v[26:27], v[12:15]
	v_mfma_f32_16x16x32_fp8_fp8 v[8:11], v[46:47], v[26:27], v[8:11]
	v_cndmask_b32_e64 v27, 0, v144, s[8:9]
	v_cndmask_b32_e64 v26, 0, v31, s[8:9]
	s_waitcnt vmcnt(13)
	s_nop 0
	v_mfma_f32_16x16x32_fp8_fp8 v[20:23], v[56:57], v[26:27], v[20:23]
	v_mfma_f32_16x16x32_fp8_fp8 v[16:19], v[58:59], v[26:27], v[16:19]
	s_waitcnt vmcnt(12)
	v_mfma_f32_16x16x32_fp8_fp8 v[12:15], v[60:61], v[26:27], v[12:15]
	v_mfma_f32_16x16x32_fp8_fp8 v[8:11], v[62:63], v[26:27], v[8:11]
	v_cndmask_b32_e64 v27, 0, v144, s[10:11]
	v_cndmask_b32_e64 v26, 0, v31, s[10:11]
	s_waitcnt vmcnt(11)
	s_nop 0
	v_mfma_f32_16x16x32_fp8_fp8 v[20:23], v[74:75], v[26:27], v[20:23]
	v_mfma_f32_16x16x32_fp8_fp8 v[16:19], v[76:77], v[26:27], v[16:19]
	s_waitcnt vmcnt(10)
	v_mfma_f32_16x16x32_fp8_fp8 v[12:15], v[78:79], v[26:27], v[12:15]
	v_mfma_f32_16x16x32_fp8_fp8 v[8:11], v[80:81], v[26:27], v[8:11]
	v_cndmask_b32_e64 v27, 0, v144, s[12:13]
	v_cndmask_b32_e64 v26, 0, v31, s[12:13]
	s_waitcnt vmcnt(9)
	s_nop 0
	v_mfma_f32_16x16x32_fp8_fp8 v[20:23], v[106:107], v[26:27], v[20:23]
	v_mfma_f32_16x16x32_fp8_fp8 v[16:19], v[108:109], v[26:27], v[16:19]
	s_waitcnt vmcnt(8)
	v_mfma_f32_16x16x32_fp8_fp8 v[12:15], v[122:123], v[26:27], v[12:15]
	v_mfma_f32_16x16x32_fp8_fp8 v[8:11], v[124:125], v[26:27], v[8:11]
	s_add_u32 s48, s0, s26
	s_addc_u32 s49, s1, s27
	global_load_dwordx4 v[40:43], v84, s[48:49]
	global_load_dwordx4 v[44:47], v84, s[48:49] offset:1024
	s_add_u32 s48, s0, s28
	s_addc_u32 s49, s1, s29
	global_load_dwordx4 v[56:59], v84, s[48:49]
	global_load_dwordx4 v[60:63], v84, s[48:49] offset:1024
	s_add_u32 s48, s0, s30
	s_addc_u32 s49, s1, s31
	global_load_dwordx4 v[74:77], v84, s[48:49]
	global_load_dwordx4 v[78:81], v84, s[48:49] offset:1024
	s_add_u32 s48, s0, s34
	s_addc_u32 s49, s1, s35
	global_load_dwordx4 v[106:109], v84, s[48:49]
	global_load_dwordx4 v[122:125], v84, s[48:49] offset:1024
	v_fmac_f32_e32 v215, v212, v24
	s_add_i32 s24, s24, 32
	s_nop 0
	v_mov_b32_e32 v212, v215
	v_mov_b32_e32 v144, v213
	s_add_i32 s32, s32, 1
	s_mov_b64 s[36:37], s[26:27]
	s_mov_b64 s[38:39], s[28:29]
	s_mov_b64 s[40:41], s[30:31]
	s_mov_b64 s[84:85], s[34:35]
	s_add_i32 s25, s32, 1
	s_cmp_lt_i32 s25, s42
	s_cbranch_scc1 .Lsl_steady
.Lsl_last:
	s_waitcnt vmcnt(23)
	v_mfma_f32_16x16x32_fp8_fp8 v[24:27], v[32:33], v[82:83], 0
	v_add_u32_e32 v150, s32, v201
	v_and_or_b32 v150, v150, 63, v73
	s_waitcnt vmcnt(22)
	v_mfma_f32_16x16x32_fp8_fp8 v[28:31], v[36:37], v[82:83], 0
	v_lshlrev_b32_e32 v150, 2, v150
	ds_bpermute_b32 v214, v150, v210
	v_mfma_f32_16x16x32_fp8_fp8 v[24:27], v[34:35], v[104:105], v[24:27]
	v_mfma_f32_16x16x32_fp8_fp8 v[28:31], v[38:39], v[104:105], v[28:31]
	s_waitcnt vmcnt(21)
	v_mfma_f32_16x16x32_fp8_fp8 v[24:27], v[48:49], v[98:99], v[24:27]
	s_waitcnt vmcnt(20)
	v_mfma_f32_16x16x32_fp8_fp8 v[28:31], v[52:53], v[98:99], v[28:31]
	v_mfma_f32_16x16x32_fp8_fp8 v[24:27], v[50:51], v[110:111], v[24:27]
	v_mfma_f32_16x16x32_fp8_fp8 v[28:31], v[54:55], v[110:111], v[28:31]
	s_waitcnt vmcnt(19)
	v_mfma_f32_16x16x32_fp8_fp8 v[24:27], v[64:65], v[100:101], v[24:27]
	s_waitcnt vmcnt(18)
	v_mfma_f32_16x16x32_fp8_fp8 v[28:31], v[68:69], v[100:101], v[28:31]
	v_mfma_f32_16x16x32_fp8_fp8 v[24:27], v[66:67], v[120:121], v[24:27]
	v_mfma_f32_16x16x32_fp8_fp8 v[28:31], v[70:71], v[120:121], v[28:31]
	s_waitcnt vmcnt(17)
	v_mfma_f32_16x16x32_fp8_fp8 v[24:27], v[112:113], v[102:103], v[24:27]
	s_waitcnt vmcnt(16)
	v_mfma_f32_16x16x32_fp8_fp8 v[28:31], v[116:117], v[102:103], v[28:31]
	v_mfma_f32_16x16x32_fp8_fp8 v[24:27], v[114:115], v[126:127], v[24:27]
	v_mfma_f32_16x16x32_fp8_fp8 v[28:31], v[118:119], v[126:127], v[28:31]

; __device__ __forceinline__ void nsa_wave(CArgs* Ap, int l, int b, int g, int tq0, const LAS float* lut, LAS float* imp, int lane) {
;     ...
;         for (int hs = h0; hs < nh; ++hs) {
;             const int s = hs >> 1, hh = hs & 1;
;             const int jm = __shfl(selreg, 16 * qi + s);
;             f32x4 acc[2];
;             acc[0] = (f32x4){0.f, 0.f, 0.f, 0.f}; acc[1] = (f32x4){0.f, 0.f, 0.f, 0.f};
; #pragma unroll
;             for (int q2 = 0; q2 < 4; ++q2) { long qm[2]; qm[0] = (qi == q2) ? q8[0] : 0l; qm[1] = (qi == q2) ? q8[1] : 0l; qk_acch8(acc, kq[q2], qm); }
;             const bool more = hs + 1 < nh; const int s1 = (hs + 1) >> 1, h1 = (hs + 1) & 1;
;             int jn[4];
; #pragma unroll
;             for (int q2 = 0; q2 < 4; ++q2) { int j = more ? __builtin_amdgcn_readlane(selreg, 16 * q2 + s1) : 0; jn[q2] = j < 0 ? 0 : j; }
;             if (more) {
; #pragma unroll
;                 for (int q2 = 0; q2 < 4; ++q2) load_kh8(kq[q2], Ks8 + (size_t)jn[q2] * 4096, h1, lane); }
;             if (__all(jm >= 0 && t - (jm * 64 + 32 * hh + 31) >= 1023)) softmax_half_far(acc, lutg, st, Od);
;             else { bf16x8 pB; softmax_half<1>(acc, (jm < 0 ? 0 : jm) * 64 + 32 * hh, jm >= 0, t, g4, lutg, st, Od, pB); }
;             const long p8 = p_to_fp8(acc);
; #pragma unroll
;             for (int q2 = 0; q2 < 4; ++q2) { const long pm = (qi == q2) ? p8 : 0l; pv_acch8(Od, vq[q2], pm); }
;             if (more) {
; #pragma unroll
;                 for (int q2 = 0; q2 < 4; ++q2) load_vh8(vq[q2], Vs8 + (size_t)jn[q2] * 4096, h1, lane); }
;         }
.Lslc_1275:
	v_sub_f32_e32 v24, v144, v213
	v_mul_f32_e32 v25, 0x43800000, v216
	v_mul_f32_e32 v26, 0x43800000, v217
	v_mul_f32_e32 v29, 0x43800000, v220
	v_mul_f32_e32 v30, 0x43800000, v221
	v_mov_b32_e32 v31, 0
	v_mov_b32_e32 v144, 0
	v_cvt_pk_fp8_f32 v144, v29, v30
	v_cvt_pk_fp8_f32 v31, v25, v26
	v_mul_f32_e32 v24, 0x3fb8aa3b, v24
	v_mul_f32_e32 v27, 0x43800000, v218
	v_mul_f32_e32 v28, 0x43800000, v219
	v_mul_f32_e32 v25, 0x43800000, v222
	v_mul_f32_e32 v26, 0x43800000, v223
	v_exp_f32_e32 v24, v24
	v_cvt_pk_fp8_f32 v144, v25, v26 op_sel:[0,0,1]
	v_cvt_pk_fp8_f32 v31, v27, v28 op_sel:[0,0,1]
	s_and_b64 vcc, exec, s[46:47]
	v_pk_mul_f32 v[22:23], v[22:23], v[24:25] op_sel_hi:[1,0]
	v_pk_mul_f32 v[20:21], v[20:21], v[24:25] op_sel_hi:[1,0]
	v_cndmask_b32_e64 v27, 0, v144, s[6:7]
	v_cndmask_b32_e64 v26, 0, v31, s[6:7]
	v_pk_mul_f32 v[18:19], v[18:19], v[24:25] op_sel_hi:[1,0]
	v_pk_mul_f32 v[16:17], v[16:17], v[24:25] op_sel_hi:[1,0]
	v_pk_mul_f32 v[14:15], v[14:15], v[24:25] op_sel_hi:[1,0]
	v_pk_mul_f32 v[12:13], v[12:13], v[24:25] op_sel_hi:[1,0]
	v_pk_mul_f32 v[10:11], v[10:11], v[24:25] op_sel_hi:[1,0]
	v_pk_mul_f32 v[8:9], v[8:9], v[24:25] op_sel_hi:[1,0]
	s_waitcnt vmcnt(7)
	s_nop 0
	v_mfma_f32_16x16x32_fp8_fp8 v[20:23], v[40:41], v[26:27], v[20:23]
	v_mfma_f32_16x16x32_fp8_fp8 v[16:19], v[42:43], v[26:27], v[16:19]
	s_waitcnt vmcnt(6)
	v_mfma_f32_16x16x32_fp8_fp8 v[12:15], v[44:45], v[26:27], v[12:15]
	v_mfma_f32_16x16x32_fp8_fp8 v[8:11], v[46:47], v[26:27], v[8:11]
	v_cndmask_b32_e64 v27, 0, v144, s[8:9]
	v_cndmask_b32_e64 v26, 0, v31, s[8:9]
	s_waitcnt vmcnt(5)
	s_nop 0
	v_mfma_f32_16x16x32_fp8_fp8 v[20:23], v[56:57], v[26:27], v[20:23]
	v_mfma_f32_16x16x32_fp8_fp8 v[16:19], v[58:59], v[26:27], v[16:19]
	s_waitcnt vmcnt(4)
	v_mfma_f32_16x16x32_fp8_fp8 v[12:15], v[60:61], v[26:27], v[12:15]
	v_mfma_f32_16x16x32_fp8_fp8 v[8:11], v[62:63], v[26:27], v[8:11]
	v_cndmask_b32_e64 v27, 0, v144, s[10:11]
	v_cndmask_b32_e64 v26, 0, v31, s[10:11]
	s_waitcnt vmcnt(3)
	s_nop 0
	v_mfma_f32_16x16x32_fp8_fp8 v[20:23], v[74:75], v[26:27], v[20:23]
	v_mfma_f32_16x16x32_fp8_fp8 v[16:19], v[76:77], v[26:27], v[16:19]
	s_waitcnt vmcnt(2)
	v_mfma_f32_16x16x32_fp8_fp8 v[12:15], v[78:79], v[26:27], v[12:15]
	v_mfma_f32_16x16x32_fp8_fp8 v[8:11], v[80:81], v[26:27], v[8:11]
	v_cndmask_b32_e64 v27, 0, v144, s[12:13]
	v_cndmask_b32_e64 v26, 0, v31, s[12:13]
	s_waitcnt vmcnt(1)
	s_nop 0
	v_mfma_f32_16x16x32_fp8_fp8 v[20:23], v[106:107], v[26:27], v[20:23]
	v_mfma_f32_16x16x32_fp8_fp8 v[16:19], v[108:109], v[26:27], v[16:19]
	s_waitcnt vmcnt(0)
	v_mfma_f32_16x16x32_fp8_fp8 v[12:15], v[122:123], v[26:27], v[12:15]
	v_mfma_f32_16x16x32_fp8_fp8 v[8:11], v[124:125], v[26:27], v[8:11]
	s_add_u32 s48, s0, s36
	s_addc_u32 s49, s1, s37
	global_load_dwordx4 v[40:43], v229, s[48:49]
	global_load_dwordx4 v[44:47], v229, s[48:49] offset:1024
	s_add_u32 s48, s0, s38
	s_addc_u32 s49, s1, s39
	global_load_dwordx4 v[56:59], v229, s[48:49]
	global_load_dwordx4 v[60:63], v229, s[48:49] offset:1024
	s_add_u32 s48, s0, s40
	s_addc_u32 s49, s1, s41
	global_load_dwordx4 v[74:77], v229, s[48:49]
	global_load_dwordx4 v[78:81], v229, s[48:49] offset:1024
	s_add_u32 s48, s0, s84
	s_addc_u32 s49, s1, s85
	global_load_dwordx4 v[106:109], v229, s[48:49]
	global_load_dwordx4 v[122:125], v229, s[48:49] offset:1024
	v_fmac_f32_e32 v215, v212, v24
	s_add_i32 s24, s24, 32
	s_nop 0
	v_mov_b32_e32 v212, v215
	v_mov_b32_e32 v144, v213
	s_waitcnt vmcnt(8)
	v_mfma_f32_16x16x32_fp8_fp8 v[24:27], v[184:185], v[82:83], 0
	v_add_u32_e32 v150, s32, v201
	v_and_or_b32 v150, v150, 63, v73
	v_mfma_f32_16x16x32_fp8_fp8 v[28:31], v[188:189], v[82:83], 0
	v_lshlrev_b32_e32 v150, 2, v150
	ds_bpermute_b32 v214, v150, v210
	v_mfma_f32_16x16x32_fp8_fp8 v[24:27], v[186:187], v[104:105], v[24:27]
	v_mfma_f32_16x16x32_fp8_fp8 v[28:31], v[190:191], v[104:105], v[28:31]
	v_mfma_f32_16x16x32_fp8_fp8 v[24:27], v[192:193], v[98:99], v[24:27]
	v_mfma_f32_16x16x32_fp8_fp8 v[28:31], v[196:197], v[98:99], v[28:31]
	v_mfma_f32_16x16x32_fp8_fp8 v[24:27], v[194:195], v[110:111], v[24:27]
	v_mfma_f32_16x16x32_fp8_fp8 v[28:31], v[198:199], v[110:111], v[28:31]
	v_mfma_f32_16x16x32_fp8_fp8 v[24:27], v[230:231], v[100:101], v[24:27]
	v_mfma_f32_16x16x32_fp8_fp8 v[28:31], v[234:235], v[100:101], v[28:31]
	v_mfma_f32_16x16x32_fp8_fp8 v[24:27], v[232:233], v[120:121], v[24:27]
	v_mfma_f32_16x16x32_fp8_fp8 v[28:31], v[236:237], v[120:121], v[28:31]
	v_mfma_f32_16x16x32_fp8_fp8 v[24:27], v[238:239], v[102:103], v[24:27]
	v_mfma_f32_16x16x32_fp8_fp8 v[28:31], v[242:243], v[102:103], v[28:31]
	v_mfma_f32_16x16x32_fp8_fp8 v[24:27], v[240:241], v[126:127], v[24:27]
	v_mfma_f32_16x16x32_fp8_fp8 v[28:31], v[244:245], v[126:127], v[28:31]

; __device__ __forceinline__ void nsa_wave(CArgs* Ap, int l, int b, int g, int tq0, const LAS float* lut, LAS float* imp, int lane) {
;     ...
;             if (__all(jm >= 0 && t - (jm * 64 + 32 * hh + 31) >= 1023)) softmax_half_far(acc, lutg, st, Od);
;             else { bf16x8 pB; softmax_half<1>(acc, (jm < 0 ? 0 : jm) * 64 + 32 * hh, jm >= 0, t, g4, lutg, st, Od, pB); }
;             const long p8 = p_to_fp8(acc);
; #pragma unroll
;             for (int q2 = 0; q2 < 4; ++q2) { const long pm = (qi == q2) ? p8 : 0l; pv_acch8(Od, vq[q2], pm); }
;             if (more) {
; #pragma unroll
;                 for (int q2 = 0; q2 < 4; ++q2) load_vh8(vq[q2], Vs8 + (size_t)jn[q2] * 4096, h1, lane); }
;         }
;         float lt = st.l; lt += __shfl_xor(lt, 16); lt += __shfl_xor(lt, 32);
.Lsld_1275:
	v_sub_f32_e32 v24, v144, v213
	v_mul_f32_e32 v25, 0x43800000, v216
	v_mul_f32_e32 v26, 0x43800000, v217
	v_mul_f32_e32 v29, 0x43800000, v220
	v_mul_f32_e32 v30, 0x43800000, v221
	v_mov_b32_e32 v31, 0
	v_mov_b32_e32 v144, 0
	v_cvt_pk_fp8_f32 v144, v29, v30
	v_cvt_pk_fp8_f32 v31, v25, v26
	v_mul_f32_e32 v24, 0x3fb8aa3b, v24
	v_mul_f32_e32 v27, 0x43800000, v218
	v_mul_f32_e32 v28, 0x43800000, v219
	v_mul_f32_e32 v25, 0x43800000, v222
	v_mul_f32_e32 v26, 0x43800000, v223
	v_exp_f32_e32 v24, v24
	v_cvt_pk_fp8_f32 v144, v25, v26 op_sel:[0,0,1]
	v_cvt_pk_fp8_f32 v31, v27, v28 op_sel:[0,0,1]
	s_and_b64 vcc, exec, s[46:47]
	v_pk_mul_f32 v[22:23], v[22:23], v[24:25] op_sel_hi:[1,0]
	v_pk_mul_f32 v[20:21], v[20:21], v[24:25] op_sel_hi:[1,0]
	v_cndmask_b32_e64 v27, 0, v144, s[6:7]
	v_cndmask_b32_e64 v26, 0, v31, s[6:7]
	v_pk_mul_f32 v[18:19], v[18:19], v[24:25] op_sel_hi:[1,0]
	v_pk_mul_f32 v[16:17], v[16:17], v[24:25] op_sel_hi:[1,0]
	v_pk_mul_f32 v[14:15], v[14:15], v[24:25] op_sel_hi:[1,0]
	v_pk_mul_f32 v[12:13], v[12:13], v[24:25] op_sel_hi:[1,0]
	v_pk_mul_f32 v[10:11], v[10:11], v[24:25] op_sel_hi:[1,0]
	v_pk_mul_f32 v[8:9], v[8:9], v[24:25] op_sel_hi:[1,0]
	s_waitcnt vmcnt(7)
	s_nop 0
	v_mfma_f32_16x16x32_fp8_fp8 v[20:23], v[40:41], v[26:27], v[20:23]
	v_mfma_f32_16x16x32_fp8_fp8 v[16:19], v[42:43], v[26:27], v[16:19]
	s_waitcnt vmcnt(6)
	v_mfma_f32_16x16x32_fp8_fp8 v[12:15], v[44:45], v[26:27], v[12:15]
	v_mfma_f32_16x16x32_fp8_fp8 v[8:11], v[46:47], v[26:27], v[8:11]
	v_cndmask_b32_e64 v27, 0, v144, s[8:9]
	v_cndmask_b32_e64 v26, 0, v31, s[8:9]
	s_waitcnt vmcnt(5)
	s_nop 0
	v_mfma_f32_16x16x32_fp8_fp8 v[20:23], v[56:57], v[26:27], v[20:23]
	v_mfma_f32_16x16x32_fp8_fp8 v[16:19], v[58:59], v[26:27], v[16:19]
	s_waitcnt vmcnt(4)
	v_mfma_f32_16x16x32_fp8_fp8 v[12:15], v[60:61], v[26:27], v[12:15]
	v_mfma_f32_16x16x32_fp8_fp8 v[8:11], v[62:63], v[26:27], v[8:11]
	v_cndmask_b32_e64 v27, 0, v144, s[10:11]
	v_cndmask_b32_e64 v26, 0, v31, s[10:11]
	s_waitcnt vmcnt(3)
	s_nop 0
	v_mfma_f32_16x16x32_fp8_fp8 v[20:23], v[74:75], v[26:27], v[20:23]
	v_mfma_f32_16x16x32_fp8_fp8 v[16:19], v[76:77], v[26:27], v[16:19]
	s_waitcnt vmcnt(2)
	v_mfma_f32_16x16x32_fp8_fp8 v[12:15], v[78:79], v[26:27], v[12:15]
	v_mfma_f32_16x16x32_fp8_fp8 v[8:11], v[80:81], v[26:27], v[8:11]
	v_cndmask_b32_e64 v27, 0, v144, s[12:13]
	v_cndmask_b32_e64 v26, 0, v31, s[12:13]
	s_waitcnt vmcnt(1)
	s_nop 0
	v_mfma_f32_16x16x32_fp8_fp8 v[20:23], v[106:107], v[26:27], v[20:23]
	v_mfma_f32_16x16x32_fp8_fp8 v[16:19], v[108:109], v[26:27], v[16:19]
	s_waitcnt vmcnt(0)
	v_mfma_f32_16x16x32_fp8_fp8 v[12:15], v[122:123], v[26:27], v[12:15]
	v_mfma_f32_16x16x32_fp8_fp8 v[8:11], v[124:125], v[26:27], v[8:11]
	v_fmac_f32_e32 v215, v212, v24
	s_add_i32 s24, s24, 32
	s_nop 0
	v_mov_b32_e32 v212, v215
	v_mov_b32_e32 v144, v213
	s_branch .LBB0_1280
